# adds: prep pooling window sums issue their (up to 16) LDS row reads back to back per output and add in the original order, instead of one read per wait
# speedup vs baseline: 1.0189x; 1.0183x over previous
.LBB0_515:
	s_or_b64 exec, exec, s[4:5]
	v_readlane_b32 s6, v253, 61
	v_readlane_b32 s7, v253, 62
	v_readlane_b32 s8, v253, 46
	s_lshl_b64 s[4:5], s[6:7], 15
	v_readlane_b32 s10, v253, 48
	v_readlane_b32 s11, v253, 49
	s_add_u32 s2, s10, s4
	s_addc_u32 s4, s11, s5
	s_add_u32 s16, s2, 0x1f6e4000
	s_addc_u32 s17, s4, 0
	v_readlane_b32 s4, v252, 52
	s_lshl_b32 s18, s6, 8
	s_lshl_b32 s20, s6, 10
	v_readlane_b32 s5, v252, 53
	s_ashr_i32 s19, s18, 31
	s_ashr_i32 s21, s20, 31
	s_andn2_b64 vcc, exec, s[4:5]
	v_readlane_b32 s9, v253, 47
	s_waitcnt lgkmcnt(0)
	s_barrier
	s_cbranch_vccnz .LBB0_570
	v_readlane_b32 s4, v253, 63
	s_mov_b32 s6, s4
	v_readlane_b32 s28, v253, 46
	s_mov_b32 s2, s6
	v_and_b32_e32 v83, 15, v82
	v_readlane_b32 s29, v253, 47
	v_readlane_b32 s30, v253, 48
	v_readlane_b32 s31, v253, 49
	v_readlane_b32 s5, v254, 0
	v_writelane_b32 v253, s2, 63
	v_lshlrev_b32_e32 v87, 3, v82
	v_lshlrev_b32_e32 v0, 11, v83
	v_writelane_b32 v254, s3, 0
	v_and_b32_e32 v11, 0xf8, v87
	v_readlane_b32 s30, v254, 1
	v_lshl_add_u64 v[4:5], s[16:17], 0, v[0:1]
	v_lshlrev_b32_e32 v0, 1, v11
	v_readlane_b32 s31, v254, 2
	v_ashrrev_i32_e32 v3, 6, v82
	v_lshlrev_b32_e32 v15, 5, v83
	v_lshl_add_u64 v[84:85], s[30:31], 0, v[0:1]
	v_lshlrev_b32_e32 v0, 4, v82
	v_and_b32_e32 v8, 0x100, v0
	v_lshlrev_b32_e32 v0, 9, v3
	v_readlane_b32 s8, v253, 36
	s_add_u32 s22, s28, 0x1112e000
	v_bfe_u32 v7, v82, 4, 2
	v_add3_u32 v16, s8, v0, v15
	v_and_b32_e32 v15, 7, v82
	v_and_b32_e32 v0, 0x3ffffff8, v82
	v_lshlrev_b32_e32 v17, 2, v0
	v_lshlrev_b32_e32 v0, 2, v15
	v_add3_u32 v130, s8, v17, v0
	v_readlane_b32 s8, v253, 58
	s_addc_u32 s23, s29, 0
	s_ashr_i32 s7, s4, 31
	s_or_b32 s4, s4, 1
	v_or_b32_e32 v90, s8, v15
	v_readlane_b32 s8, v254, 11
	s_ashr_i32 s5, s4, 31
	v_lshlrev_b32_e32 v9, 3, v7
	v_ashrrev_i32_e32 v14, 7, v82
	v_readlane_b32 s9, v254, 12
	s_lshl_b64 s[26:27], s[4:5], 12
	s_or_b32 s4, s6, 2
	v_lshl_or_b32 v2, v3, 7, v9
	v_lshl_add_u64 v[92:93], s[8:9], 0, v[0:1]
	v_lshlrev_b32_e32 v0, 5, v3
	v_lshlrev_b32_e32 v3, 6, v14
	v_readlane_b32 s15, v253, 37
	s_ashr_i32 s5, s4, 31
	v_lshlrev_b32_e32 v126, 2, v14
	v_mov_b32_e32 v14, s15
	s_movk_i32 s10, 0x210
	v_and_or_b32 v18, v0, 32, v3
	s_lshl_b64 s[38:39], s[4:5], 12
	s_or_b32 s4, s6, 3
	v_and_b32_e32 v13, 31, v82
	v_mad_u32_u24 v14, v83, s10, v14
	v_or_b32_e32 v94, v18, v9
	v_readlane_b32 s10, v254, 3
	s_ashr_i32 s5, s4, 31
	v_and_b32_e32 v6, 24, v87
	v_ashrrev_i32_e32 v95, 31, v94
	v_readlane_b32 s11, v254, 4
	v_cmp_gt_u32_e32 vcc, 16, v13
	v_mov_b32_e32 v0, 0x3e000000
	v_ashrrev_i32_e32 v3, 31, v2
	s_lshl_b64 s[40:41], s[4:5], 12
	v_cmp_gt_u32_e64 s[4:5], 2, v7
	v_lshlrev_b32_e32 v7, 4, v7
	v_and_b32_e32 v15, 0xffffff80, v82
	v_lshl_add_u64 v[96:97], v[94:95], 1, s[10:11]
	v_cndmask_b32_e32 v98, 1.0, v0, vcc
	s_mov_b32 s10, 0x1fffffe0
	v_lshlrev_b32_e32 v0, 2, v6
	v_lshlrev_b64 v[2:3], 1, v[2:3]
	v_and_b32_e32 v12, 0x3f8, v87
	v_add3_u32 v131, v14, v15, v7
	v_and_or_b32 v9, v82, s10, v6
	v_lshl_add_u64 v[14:15], s[28:29], 0, v[0:1]
	s_mov_b64 s[10:11], 0x812e000
	v_lshl_add_u64 v[106:107], v[4:5], 0, v[2:3]
	v_add_u32_e32 v4, 0x200, v82
	s_add_i32 s2, 0, 0x10000
	v_lshl_add_u64 v[100:101], v[14:15], 0, s[10:11]
	v_lshlrev_b32_e32 v14, 2, v12
	v_mov_b32_e32 v15, v1
	v_ashrrev_i32_e32 v132, 5, v4
	v_lshlrev_b32_e32 v4, 5, v4
	v_lshl_add_u32 v11, v11, 2, s2
	v_lshl_add_u64 v[14:15], s[28:29], 0, v[14:15]
	s_mov_b64 s[10:11], 0x1a12e000
	v_and_b32_e32 v4, 0xfffffc00, v4
	v_lshlrev_b32_e32 v0, 1, v12
	v_lshl_add_u64 v[104:105], v[14:15], 0, s[10:11]
	v_and_b32_e32 v14, 0xff, v82
	v_lshlrev_b32_e32 v5, 5, v82
	v_add_u32_e32 v134, v11, v4
	v_bfe_u32 v4, v82, 6, 2
	v_lshl_add_u64 v[102:103], s[28:29], 0, v[0:1]
	v_and_b32_e32 v5, 0xfffffc00, v5
	v_lshlrev_b32_e64 v135, v4, 2
	v_or_b32_e32 v4, v18, v83
	v_lshl_add_u64 v[110:111], s[30:31], 0, v[0:1]
	v_lshlrev_b32_e32 v0, 2, v14
	s_lshl_b64 s[24:25], s[6:7], 12
	v_bfe_u32 v86, v82, 2, 2
	s_add_i32 s6, 0, 0x1cc00
	v_add_u32_e32 v133, v11, v5
	v_lshl_add_u32 v136, v14, 1, s15
	v_mul_lo_u32 v4, v4, s14
	v_lshlrev_b32_e32 v5, 3, v9
	v_readlane_b32 s14, v253, 44
	v_add_u32_e32 v140, s2, v0
	v_readlane_b32 s2, v253, 38
	v_lshlrev_b32_e32 v10, 6, v86
	v_lshl_add_u32 v128, v13, 2, s6
	s_movk_i32 s6, 0x80
	s_movk_i32 s8, 0x1000
	v_add_u32_e32 v17, 0, v7
	v_cmp_lt_u32_e32 vcc, 15, v13
	s_movk_i32 s10, 0x3e0
	s_movk_i32 s12, 0x1e0
	v_readlane_b32 s15, v253, 45
	v_add_u32_e32 v141, s2, v0
	v_add_u32_e32 v0, 0, v5
	v_ashrrev_i32_e32 v89, 5, v82
	v_lshlrev_b32_e32 v88, 3, v13
	v_add_u32_e32 v127, -3, v126
	v_cmp_gt_i32_e64 s[6:7], s6, v82
	v_ashrrev_i32_e32 v129, 3, v82
	v_ashrrev_i32_e32 v91, 31, v90
	v_cmp_gt_i32_e64 s[8:9], s8, v82
	v_cmp_gt_i32_e64 s[10:11], s10, v82
	v_cmp_gt_i32_e64 s[12:13], s12, v82
	v_or_b32_e32 v137, 1, v126
	v_or_b32_e32 v138, 2, v126
	v_or_b32_e32 v139, 3, v126
	v_mov_b32_e32 v99, v98
	v_lshl_add_u64 v[108:109], s[14:15], 0, v[2:3]
	v_lshlrev_b32_e32 v112, 1, v8
	v_lshlrev_b32_e32 v114, 1, v10
	v_lshlrev_b32_e32 v116, 1, v6
	v_add_u32_e32 v142, v16, v7
	v_lshlrev_b32_e32 v118, 2, v14
	v_add_u32_e32 v143, v17, v4
	v_add_u32_e32 v144, 0x1bc00, v0
	s_xor_b64 s[42:43], vcc, -1
	v_lshlrev_b32_e32 v120, 2, v12
	v_readlane_b32 s98, v253, 42
	v_readlane_b32 s99, v253, 43
	v_mov_b32_e32 v218, v120
	v_mov_b32_e32 v219, v1
	s_load_dwordx2 s[100:101], s[98:99], 0x78
	s_lshl_b64 s[14:15], s[20:21], 2
	s_waitcnt lgkmcnt(0)
	v_lshl_add_u64 v[218:219], s[100:101], 0, v[218:219]
	s_load_dwordx2 s[100:101], s[98:99], 0x80
	v_lshl_add_u64 v[220:221], v[218:219], 0, s[24:25]
	global_load_dwordx4 v[156:159], v[220:221], off offset:16
	global_load_dwordx4 v[160:163], v[220:221], off
	v_lshl_add_u64 v[220:221], v[218:219], 0, s[26:27]
	global_load_dwordx4 v[164:167], v[220:221], off offset:16
	global_load_dwordx4 v[168:171], v[220:221], off
	v_lshl_add_u64 v[220:221], v[218:219], 0, s[38:39]
	global_load_dwordx4 v[172:175], v[220:221], off offset:16
	global_load_dwordx4 v[176:179], v[220:221], off
	v_lshl_add_u64 v[220:221], v[218:219], 0, s[40:41]
	global_load_dwordx4 v[180:183], v[220:221], off offset:16
	global_load_dwordx4 v[184:187], v[220:221], off
	s_waitcnt lgkmcnt(0)
	s_add_u32 s14, s100, s14
	s_addc_u32 s15, s101, s15
	s_load_dwordx2 s[100:101], s[98:99], 0x70
	s_nop 0
	global_load_dwordx4 v[148:151], v120, s[14:15] offset:16
	global_load_dwordx4 v[152:155], v120, s[14:15]
	s_lshl_b64 s[14:15], s[18:19], 2
	s_waitcnt lgkmcnt(0)
	s_add_u32 s14, s100, s14
	s_addc_u32 s15, s101, s15
	s_load_dwordx2 s[100:101], s[98:99], 0x88
	v_lshl_add_u64 v[220:221], v[94:95], 2, s[14:15]
	global_load_dwordx4 v[188:191], v[220:221], off offset:16
	global_load_dwordx4 v[196:199], v[220:221], off
	s_waitcnt lgkmcnt(0)
	v_lshl_add_u64 v[220:221], v[90:91], 2, s[100:101]
	global_load_dword v192, v[220:221], off
	s_waitcnt vmcnt(0)
	v_readlane_b32 s2, v252, 50
	s_branch .LBB0_518
	s_nop 0
	s_nop 0
	s_nop 0
	s_nop 0
	s_nop 0
	s_nop 0
	s_nop 0
	s_nop 0
	s_nop 0
	s_nop 0
	s_nop 0
	s_nop 0
	s_nop 0
	s_nop 0
	s_nop 0
	s_nop 0
	s_nop 0
	s_nop 0
	s_nop 0
	s_nop 0
	s_nop 0

.LBB0_550:
	v_ashrrev_i32_e32 v0, 8, v42
	v_lshl_add_u32 v44, v0, 10, v141
	v_mov_b32_e32 v43, 0
	v_add_u32_e32 v44, 0xffffc400, v44
	ds_read_b32 v202, v44 offset:15360
	ds_read_b32 v203, v44 offset:14336
	ds_read_b32 v204, v44 offset:13312
	ds_read_b32 v205, v44 offset:12288
	ds_read_b32 v206, v44 offset:11264
	ds_read_b32 v207, v44 offset:10240
	ds_read_b32 v208, v44 offset:9216
	ds_read_b32 v209, v44 offset:8192
	ds_read_b32 v210, v44 offset:7168
	ds_read_b32 v211, v44 offset:6144
	ds_read_b32 v212, v44 offset:5120
	ds_read_b32 v213, v44 offset:4096
	ds_read_b32 v214, v44 offset:3072
	ds_read_b32 v215, v44 offset:2048
	ds_read_b32 v216, v44 offset:1024
	ds_read_b32 v217, v44
	v_readfirstlane_b32 s98, v135
	s_waitcnt lgkmcnt(0)
	v_add_f32_e32 v43, v43, v202
	v_add_f32_e32 v43, v43, v203
	s_cmp_lt_u32 s98, 3
	s_cbranch_scc1 .Lpoolsum_done
	v_add_f32_e32 v43, v43, v204
	v_add_f32_e32 v43, v43, v205
	s_cmp_lt_u32 s98, 5
	s_cbranch_scc1 .Lpoolsum_done
	v_add_f32_e32 v43, v43, v206
	v_add_f32_e32 v43, v43, v207
	v_add_f32_e32 v43, v43, v208
	v_add_f32_e32 v43, v43, v209
	s_cmp_lt_u32 s98, 9
	s_cbranch_scc1 .Lpoolsum_done
	v_add_f32_e32 v43, v43, v210
	v_add_f32_e32 v43, v43, v211
	v_add_f32_e32 v43, v43, v212
	v_add_f32_e32 v43, v43, v213
	v_add_f32_e32 v43, v43, v214
	v_add_f32_e32 v43, v43, v215
	v_add_f32_e32 v43, v43, v216
	v_add_f32_e32 v43, v43, v217
.Lpoolsum_done:
	v_add_u32_e32 v45, s44, v0
	v_add_u32_e32 v44, 1, v45
	v_min_i32_e32 v44, v44, v135
	v_cvt_f32_i32_e32 v46, v44
	v_and_b32_e32 v44, 0x3fffff00, v42
	v_lshl_add_u32 v44, v44, 2, v140
	ds_read_b32 v44, v44 offset:15360
	v_div_scale_f32 v47, s[36:37], v46, v46, v43
	v_rcp_f32_e32 v48, v47
	v_div_scale_f32 v49, vcc, v43, v46, v43
	s_movk_i32 s36, 0x210
	v_fma_f32 v51, -v47, v48, 1.0
	v_fmac_f32_e32 v48, v51, v48
	v_mul_f32_e32 v51, v49, v48
	v_fma_f32 v52, -v47, v51, v49
	v_fmac_f32_e32 v51, v52, v48
	v_fma_f32 v47, -v47, v51, v49
	v_div_fmas_f32 v47, v47, v48, v51
	v_div_fixup_f32 v43, v47, v46, v43
	v_mad_i32_i24 v0, v0, s36, v136
	s_movk_i32 s36, 0x1ff0
	s_waitcnt lgkmcnt(0)
	v_sub_f32_e32 v43, v43, v44
	v_cmp_lt_i32_e32 vcc, s36, v45
	v_cvt_pk_bf16_f32 v43, v43, v1
	ds_write_b16 v0, v43
	s_and_saveexec_b64 s[36:37], vcc
	s_cbranch_execz .LBB0_549
	v_add_u32_e32 v0, 0xffffe00f, v45
	v_lshl_add_u64 v[46:47], s[28:29], 0, v[0:1]
	v_readlane_b32 s48, v253, 46
	v_lshlrev_b64 v[46:47], 10, v[46:47]
	v_readlane_b32 s49, v253, 47
	v_mov_b32_e32 v119, v1
	v_readlane_b32 s50, v253, 48
	v_lshl_add_u64 v[46:47], s[48:49], 0, v[46:47]
	v_lshl_add_u64 v[46:47], v[46:47], 0, v[118:119]
	v_add_co_u32_e32 v46, vcc, 0x8020000, v46
	v_readlane_b32 s51, v253, 49
	s_nop 0
	v_addc_co_u32_e32 v47, vcc, 0, v47, vcc
	global_store_dword v[46:47], v44, off
	s_branch .LBB0_549
